# combo13 = combo10 + non-temporal policy on the final phase's once-read x/delta loads and once-written output stores
# speedup vs baseline: 1.0018x; 1.0010x over previous
.LBB0_1888:
	flat_load_dwordx2 v[16:17], v[10:11] nt
	flat_load_dwordx2 v[56:57], v[10:11] offset:512 nt
	flat_load_dwordx2 v[58:59], v[10:11] offset:1024 nt
	flat_load_dwordx2 v[60:61], v[10:11] offset:1536 nt
	flat_load_dwordx2 v[62:63], v[10:11] offset:2048 nt
	flat_load_dwordx2 v[64:65], v[10:11] offset:2560 nt
	flat_load_dwordx2 v[66:67], v[10:11] offset:3072 nt
	flat_load_dwordx2 v[68:69], v[10:11] offset:3584 nt
	flat_load_dwordx4 v[20:23], v[12:13] nt
	flat_load_dwordx4 v[24:27], v[12:13] offset:1024 nt
	flat_load_dwordx4 v[28:31], v[12:13] offset:2048 nt
	flat_load_dwordx4 v[32:35], v[12:13] offset:3072 nt
	v_add_co_u32_e32 v14, vcc, s3, v12
	s_add_i32 s2, s2, s4
	s_nop 0
	v_addc_co_u32_e32 v15, vcc, 0, v13, vcc
	flat_load_dwordx4 v[36:39], v[0:1]
	flat_load_dwordx4 v[40:43], v[14:15] nt
	flat_load_dwordx4 v[44:47], v[14:15] offset:1024 nt
	flat_load_dwordx4 v[48:51], v[14:15] offset:2048 nt
	flat_load_dwordx4 v[52:55], v[14:15] offset:3072 nt
	v_lshl_add_u64 v[10:11], v[10:11], 0, s[6:7]
	s_cmp_lt_i32 s2, 0x8000
	s_waitcnt vmcnt(0) lgkmcnt(0)
	v_lshlrev_b32_e32 v70, 16, v16
	v_and_b32_e32 v71, 0xffff0000, v16
	v_lshlrev_b32_e32 v16, 16, v17
	v_and_b32_e32 v17, 0xffff0000, v17
	v_lshlrev_b32_e32 v72, 16, v56
	v_and_b32_e32 v73, 0xffff0000, v56
	v_lshlrev_b32_e32 v56, 16, v57
	v_and_b32_e32 v57, 0xffff0000, v57
	v_lshlrev_b32_e32 v74, 16, v58
	v_and_b32_e32 v75, 0xffff0000, v58
	v_lshlrev_b32_e32 v58, 16, v59
	v_and_b32_e32 v59, 0xffff0000, v59
	v_lshlrev_b32_e32 v76, 16, v60
	v_and_b32_e32 v77, 0xffff0000, v60
	v_lshlrev_b32_e32 v60, 16, v61
	v_and_b32_e32 v61, 0xffff0000, v61
	v_pk_add_f32 v[16:17], v[22:23], v[16:17]
	v_pk_add_f32 v[20:21], v[20:21], v[70:71]
	v_pk_add_f32 v[26:27], v[26:27], v[56:57]
	v_pk_add_f32 v[24:25], v[24:25], v[72:73]
	v_lshlrev_b32_e32 v78, 16, v62
	v_and_b32_e32 v79, 0xffff0000, v62
	v_lshlrev_b32_e32 v62, 16, v63
	v_and_b32_e32 v63, 0xffff0000, v63
	v_lshlrev_b32_e32 v80, 16, v64
	v_and_b32_e32 v81, 0xffff0000, v64
	v_lshlrev_b32_e32 v64, 16, v65
	v_and_b32_e32 v65, 0xffff0000, v65
	v_pk_add_f32 v[28:29], v[28:29], v[74:75]
	v_pk_add_f32 v[30:31], v[30:31], v[58:59]
	v_pk_add_f32 v[34:35], v[34:35], v[60:61]
	v_mov_b32_e32 v56, v21
	v_mov_b32_e32 v57, v25
	v_mov_b32_e32 v60, v17
	v_mov_b32_e32 v61, v27
	v_pk_add_f32 v[42:43], v[42:43], v[62:63]
	v_pk_add_f32 v[46:47], v[46:47], v[64:65]
	v_mov_b32_e32 v22, v20
	v_mov_b32_e32 v23, v24
	v_mov_b32_e32 v58, v16
	v_mov_b32_e32 v59, v26
	v_pk_mul_f32 v[62:63], v[30:31], v[30:31]
	v_pk_mul_f32 v[64:65], v[28:29], v[28:29]
	v_pk_mul_f32 v[56:57], v[56:57], v[56:57]
	v_pk_mul_f32 v[60:61], v[60:61], v[60:61]
	v_lshlrev_b32_e32 v82, 16, v66
	v_and_b32_e32 v83, 0xffff0000, v66
	v_lshlrev_b32_e32 v66, 16, v67
	v_and_b32_e32 v67, 0xffff0000, v67
	v_lshlrev_b32_e32 v84, 16, v68
	v_and_b32_e32 v85, 0xffff0000, v68
	v_lshlrev_b32_e32 v68, 16, v69
	v_and_b32_e32 v69, 0xffff0000, v69
	v_pk_add_f32 v[32:33], v[32:33], v[76:77]
	v_pk_add_f32 v[40:41], v[40:41], v[78:79]
	v_pk_mov_b32 v[78:79], v[64:65], v[62:63] op_sel:[1,0]
	v_mov_b32_e32 v65, v63
	v_pk_fma_f32 v[22:23], v[22:23], v[22:23], v[56:57]
	v_pk_fma_f32 v[56:57], v[58:59], v[58:59], v[60:61]
	v_pk_add_f32 v[50:51], v[50:51], v[66:67]
	v_pk_add_f32 v[54:55], v[54:55], v[68:69]
	v_mul_f32_e32 v66, v33, v33
	v_mul_f32_e32 v68, v35, v35
	v_pk_add_f32 v[58:59], v[78:79], v[64:65]
	v_pk_add_f32 v[22:23], v[22:23], v[56:57]
	v_pk_add_f32 v[44:45], v[44:45], v[80:81]
	v_pk_add_f32 v[48:49], v[48:49], v[82:83]
	v_mul_f32_e32 v77, v40, v40
	v_mul_f32_e32 v80, v41, v41
	v_mul_f32_e32 v81, v42, v42
	v_mul_f32_e32 v82, v43, v43
	v_pk_fma_f32 v[62:63], v[32:33], v[32:33], v[66:67] op_sel_hi:[1,1,0]
	v_pk_fma_f32 v[66:67], v[34:35], v[34:35], v[68:69] op_sel_hi:[1,1,0]
	v_pk_add_f32 v[56:57], v[58:59], v[58:59] op_sel:[0,1] op_sel_hi:[1,0]
	v_pk_add_f32 v[22:23], v[22:23], v[22:23] op_sel:[0,1] op_sel_hi:[1,0]
	v_pk_mul_f32 v[70:71], v[44:45], v[44:45]
	v_pk_mul_f32 v[72:73], v[46:47], v[46:47]
	v_mov_b32_e32 v63, v81
	v_mov_b32_e32 v67, v82
	v_mov_b32_e32 v57, v80
	v_mov_b32_e32 v23, v77
	v_pk_mov_b32 v[68:69], v[70:71], v[72:73] op_sel:[1,0]
	v_mov_b32_e32 v71, v73
	v_pk_add_f32 v[58:59], v[62:63], v[66:67]
	v_pk_add_f32 v[22:23], v[22:23], v[56:57]
	v_pk_add_f32 v[52:53], v[52:53], v[84:85]
	v_mul_f32_e32 v74, v49, v49
	v_mul_f32_e32 v76, v51, v51
	v_pk_add_f32 v[60:61], v[68:69], v[70:71]
	v_pk_add_f32 v[22:23], v[22:23], v[58:59]
	v_mul_f32_e32 v83, v52, v52
	v_mul_f32_e32 v84, v53, v53
	v_mul_f32_e32 v85, v54, v54
	v_mul_f32_e32 v86, v55, v55
	v_pk_fma_f32 v[72:73], v[48:49], v[48:49], v[74:75] op_sel_hi:[1,1,0]
	v_pk_fma_f32 v[74:75], v[50:51], v[50:51], v[76:77] op_sel_hi:[1,1,0]
	v_pk_add_f32 v[60:61], v[60:61], v[60:61] op_sel:[0,1] op_sel_hi:[1,0]
	v_pk_add_f32 v[22:23], v[22:23], v[22:23] op_sel:[0,1] op_sel_hi:[1,0]
	v_mov_b32_e32 v73, v85
	v_mov_b32_e32 v75, v86
	v_mov_b32_e32 v61, v84
	v_mov_b32_e32 v23, v83
	v_pk_add_f32 v[62:63], v[72:73], v[74:75]
	v_pk_add_f32 v[22:23], v[22:23], v[60:61]
	s_nop 0
	v_pk_add_f32 v[22:23], v[22:23], v[62:63]
	s_nop 0
	v_add_f32_e32 v22, v22, v23
	s_nop 1
	v_add_f32_dpp v22, v22, v22 quad_perm:[1,0,3,2] row_mask:0xf bank_mask:0xf bound_ctrl:1
	s_nop 1
	v_add_f32_dpp v22, v22, v22 quad_perm:[2,3,0,1] row_mask:0xf bank_mask:0xf bound_ctrl:1
	s_nop 1
	v_add_f32_dpp v22, v22, v22 row_half_mirror row_mask:0xf bank_mask:0xf bound_ctrl:1
	s_nop 1
	v_add_f32_dpp v22, v22, v22 row_mirror row_mask:0xf bank_mask:0xf bound_ctrl:1
	s_nop 0
	v_readlane_b32 s10, v22, 16
	v_readlane_b32 s11, v22, 48
	v_readlane_b32 s0, v22, 0
	v_readlane_b32 s1, v22, 32
	v_mov_b32_e32 v22, s10
	v_mov_b32_e32 v23, s11
	v_pk_add_f32 v[22:23], s[0:1], v[22:23]
	s_nop 0
	v_add_f32_e32 v22, v22, v23
	v_fmamk_f32 v22, v22, 0x3a000000, v18
	v_mul_f32_e32 v23, 0x4f800000, v22
	v_cmp_gt_f32_e32 vcc, s5, v22
	s_nop 1
	v_cndmask_b32_e32 v22, v22, v23, vcc
	v_sqrt_f32_e32 v23, v22
	s_nop 0
	v_add_u32_e32 v56, -1, v23
	v_add_u32_e32 v57, 1, v23
	v_fma_f32 v58, -v56, v23, v22
	v_fma_f32 v59, -v57, v23, v22
	v_cmp_ge_f32_e64 s[0:1], 0, v58
	s_nop 1
	v_cndmask_b32_e64 v23, v23, v56, s[0:1]
	v_cmp_lt_f32_e64 s[0:1], 0, v59
	s_nop 1
	v_cndmask_b32_e64 v23, v23, v57, s[0:1]
	v_mul_f32_e32 v56, 0x37800000, v23
	v_cndmask_b32_e32 v23, v23, v56, vcc
	v_cmp_class_f32_e32 vcc, v22, v19
	s_nop 1
	v_cndmask_b32_e32 v22, v23, v22, vcc
	v_div_scale_f32 v23, s[0:1], v22, v22, 1.0
	v_rcp_f32_e32 v57, v23
	v_div_scale_f32 v56, vcc, 1.0, v22, 1.0
	v_fma_f32 v58, -v23, v57, 1.0
	v_fmac_f32_e32 v57, v58, v57
	v_mul_f32_e32 v58, v56, v57
	v_fma_f32 v59, -v23, v58, v56
	v_fmac_f32_e32 v58, v59, v57
	v_fma_f32 v23, -v23, v58, v56
	v_div_fmas_f32 v23, v23, v57, v58
	v_div_fixup_f32 v56, v23, v22, 1.0
	v_pk_mul_f32 v[20:21], v[20:21], v[56:57] op_sel_hi:[1,0]
	v_pk_mul_f32 v[16:17], v[16:17], v[56:57] op_sel_hi:[1,0]
	v_pk_mul_f32 v[20:21], v[36:37], v[20:21]
	v_pk_mul_f32 v[22:23], v[38:39], v[16:17]
	flat_store_dwordx4 v[12:13], v[20:23] nt
	flat_load_dwordx4 v[20:23], v[0:1] offset:1024
	v_pk_mul_f32 v[16:17], v[26:27], v[56:57] op_sel_hi:[1,0]
	v_pk_mul_f32 v[24:25], v[24:25], v[56:57] op_sel_hi:[1,0]
	s_waitcnt vmcnt(0) lgkmcnt(0)
	v_pk_mul_f32 v[22:23], v[22:23], v[16:17]
	v_pk_mul_f32 v[20:21], v[20:21], v[24:25]
	flat_store_dwordx4 v[12:13], v[20:23] offset:1024 nt
	flat_load_dwordx4 v[20:23], v[0:1] offset:2048
	v_pk_mul_f32 v[16:17], v[30:31], v[56:57] op_sel_hi:[1,0]
	v_pk_mul_f32 v[24:25], v[28:29], v[56:57] op_sel_hi:[1,0]
	s_waitcnt vmcnt(0) lgkmcnt(0)
	v_pk_mul_f32 v[22:23], v[22:23], v[16:17]
	v_pk_mul_f32 v[20:21], v[20:21], v[24:25]
	flat_store_dwordx4 v[12:13], v[20:23] offset:2048 nt
	flat_load_dwordx4 v[20:23], v[0:1] offset:3072
	v_pk_mul_f32 v[16:17], v[34:35], v[56:57] op_sel_hi:[1,0]
	v_pk_mul_f32 v[24:25], v[32:33], v[56:57] op_sel_hi:[1,0]
	s_waitcnt vmcnt(0) lgkmcnt(0)
	v_pk_mul_f32 v[22:23], v[22:23], v[16:17]
	v_pk_mul_f32 v[20:21], v[20:21], v[24:25]
	flat_store_dwordx4 v[12:13], v[20:23] offset:3072 nt
	flat_load_dwordx4 v[20:23], v[2:3]
	v_pk_mul_f32 v[16:17], v[42:43], v[56:57] op_sel_hi:[1,0]
	v_pk_mul_f32 v[24:25], v[40:41], v[56:57] op_sel_hi:[1,0]
	v_lshl_add_u64 v[12:13], v[12:13], 0, s[8:9]
	s_waitcnt vmcnt(0) lgkmcnt(0)
	v_pk_mul_f32 v[20:21], v[24:25], v[20:21]
	v_pk_mul_f32 v[22:23], v[16:17], v[22:23]
	flat_store_dwordx4 v[14:15], v[20:23] nt
	flat_load_dwordx4 v[20:23], v[4:5]
	v_pk_mul_f32 v[16:17], v[46:47], v[56:57] op_sel_hi:[1,0]
	v_pk_mul_f32 v[24:25], v[44:45], v[56:57] op_sel_hi:[1,0]
	s_waitcnt vmcnt(0) lgkmcnt(0)
	v_pk_mul_f32 v[22:23], v[16:17], v[22:23]
	v_pk_mul_f32 v[20:21], v[24:25], v[20:21]
	flat_store_dwordx4 v[14:15], v[20:23] offset:1024 nt
	flat_load_dwordx4 v[20:23], v[6:7]
	v_pk_mul_f32 v[16:17], v[50:51], v[56:57] op_sel_hi:[1,0]
	v_pk_mul_f32 v[24:25], v[48:49], v[56:57] op_sel_hi:[1,0]
	s_waitcnt vmcnt(0) lgkmcnt(0)
	v_pk_mul_f32 v[22:23], v[16:17], v[22:23]
	v_pk_mul_f32 v[20:21], v[24:25], v[20:21]
	flat_store_dwordx4 v[14:15], v[20:23] offset:2048 nt
	flat_load_dwordx4 v[20:23], v[8:9]
	v_pk_mul_f32 v[16:17], v[54:55], v[56:57] op_sel_hi:[1,0]
	v_pk_mul_f32 v[24:25], v[52:53], v[56:57] op_sel_hi:[1,0]
	s_waitcnt vmcnt(0) lgkmcnt(0)
	v_pk_mul_f32 v[22:23], v[16:17], v[22:23]
	v_pk_mul_f32 v[20:21], v[24:25], v[20:21]
	flat_store_dwordx4 v[14:15], v[20:23] offset:3072 nt
	s_cbranch_scc1 .LBB0_1888
